# attention output epilogue: v_permlane32_swap pairs -> 8 dwordx4 stores instead of 16 dwordx2 per lane
# speedup vs baseline: 1.0035x; 1.0035x over previous
; __device__ __forceinline__ unsigned cvt_pk_bf16(float lo, float hi) { unsigned r; asm volatile("v_cvt_pk_bf16_f32 %0, %1, %2" : "=v"(r) : "v"(lo), "v"(hi)); return r; }
; __device__ __forceinline__ void attn_unit(LAS unsigned char* lds, const bf16_t* QK, const bf16_t* VTt, const float* KM, bf16_t* OA, int b, int h, int qb, int tid, int lane, int wave) {
;     ...
;     const float inv = 1.f / (lrun + __shfl_xor(lrun, 32));
;     bf16_t* op = OA + (size_t)(row0 + r32) * D + h * HD + hf * 4;
; #pragma unroll
;     for (int db = 0; db < 4; ++db)
; #pragma unroll
;         for (int rg = 0; rg < 4; ++rg) { u32x2 w; w.x = cvt_pk_bf16(o[db][4 * rg] * inv, o[db][4 * rg + 1] * inv); w.y = cvt_pk_bf16(o[db][4 * rg + 2] * inv, o[db][4 * rg + 3] * inv);
;             *(u32x2*)(op + db * 32 + rg * 8) = w; }
.LBB0_1512:
	ds_bpermute_b32 v1, v219, v211
	v_lshlrev_b64 v[2:3], 11, v[216:217]
	v_lshl_add_u64 v[2:3], s[18:19], 0, v[2:3]
	v_lshl_add_u64 v[2:3], v[2:3], 0, s[44:45]
	s_add_i32 s3, s3, s22
	s_waitcnt lgkmcnt(0)
	v_add_f32_e32 v1, v211, v1
	v_div_scale_f32 v4, s[0:1], v1, v1, 1.0
	v_rcp_f32_e32 v5, v4
	v_div_scale_f32 v6, vcc, 1.0, v1, 1.0
	v_mov_b32_e32 v211, v0
	v_fma_f32 v7, -v4, v5, 1.0
	v_fmac_f32_e32 v5, v7, v5
	v_mul_f32_e32 v7, v6, v5
	v_fma_f32 v8, -v4, v7, v6
	v_fmac_f32_e32 v7, v8, v5
	v_fma_f32 v4, -v4, v7, v6
	v_div_fmas_f32 v4, v4, v5, v7
	v_div_fixup_f32 v1, v4, v1, 1.0
	v_lshl_add_u64 v[2:3], v[2:3], 0, v[210:211]
	v_and_b32_e32 v88, 32, v196
	v_lshrrev_b32_e32 v88, 2, v88
	v_mov_b32_e32 v89, 0
	v_lshl_add_u64 v[2:3], v[2:3], 0, v[88:89]
	v_mul_f32_e32 v80, v64, v1
	v_mul_f32_e32 v81, v65, v1
	v_cvt_pk_bf16_f32 v84, v80, v81
	v_mul_f32_e32 v82, v66, v1
	v_mul_f32_e32 v83, v67, v1
	v_cvt_pk_bf16_f32 v85, v82, v83
	v_mul_f32_e32 v80, v68, v1
	v_mul_f32_e32 v81, v69, v1
	v_cvt_pk_bf16_f32 v86, v80, v81
	v_mul_f32_e32 v82, v70, v1
	v_mul_f32_e32 v83, v71, v1
	v_cvt_pk_bf16_f32 v87, v82, v83
	s_nop 1
	v_permlane32_swap_b32_e32 v84, v86
	v_permlane32_swap_b32_e32 v85, v87
	global_store_dwordx4 v[2:3], v[84:87], off
	s_add_i32 s65, s65, s22
	s_cmpk_lt_i32 s3, 0x200
	v_mul_f32_e32 v80, v72, v1
	v_mul_f32_e32 v81, v73, v1
	v_cvt_pk_bf16_f32 v84, v80, v81
	v_mul_f32_e32 v82, v74, v1
	v_mul_f32_e32 v83, v75, v1
	v_cvt_pk_bf16_f32 v85, v82, v83
	v_mul_f32_e32 v80, v76, v1
	v_mul_f32_e32 v81, v77, v1
	v_cvt_pk_bf16_f32 v86, v80, v81
	v_mul_f32_e32 v82, v78, v1
	v_mul_f32_e32 v83, v79, v1
	v_cvt_pk_bf16_f32 v87, v82, v83
	s_nop 1
	v_permlane32_swap_b32_e32 v84, v86
	v_permlane32_swap_b32_e32 v85, v87
	global_store_dwordx4 v[2:3], v[84:87], off offset:32
	v_mul_f32_e32 v80, v48, v1
	v_mul_f32_e32 v81, v49, v1
	v_cvt_pk_bf16_f32 v84, v80, v81
	v_mul_f32_e32 v82, v50, v1
	v_mul_f32_e32 v83, v51, v1
	v_cvt_pk_bf16_f32 v85, v82, v83
	v_mul_f32_e32 v80, v52, v1
	v_mul_f32_e32 v81, v53, v1
	v_cvt_pk_bf16_f32 v86, v80, v81
	v_mul_f32_e32 v82, v54, v1
	v_mul_f32_e32 v83, v55, v1
	v_cvt_pk_bf16_f32 v87, v82, v83
	s_nop 1
	v_permlane32_swap_b32_e32 v84, v86
	v_permlane32_swap_b32_e32 v85, v87
	global_store_dwordx4 v[2:3], v[84:87], off offset:64
	v_mul_f32_e32 v80, v56, v1
	v_mul_f32_e32 v81, v57, v1
	v_cvt_pk_bf16_f32 v84, v80, v81
	v_mul_f32_e32 v82, v58, v1
	v_mul_f32_e32 v83, v59, v1
	v_cvt_pk_bf16_f32 v85, v82, v83
	v_mul_f32_e32 v80, v60, v1
	v_mul_f32_e32 v81, v61, v1
	v_cvt_pk_bf16_f32 v86, v80, v81
	v_mul_f32_e32 v82, v62, v1
	v_mul_f32_e32 v83, v63, v1
	v_cvt_pk_bf16_f32 v87, v82, v83
	s_nop 1
	v_permlane32_swap_b32_e32 v84, v86
	v_permlane32_swap_b32_e32 v85, v87
	global_store_dwordx4 v[2:3], v[84:87], off offset:96
	v_mul_f32_e32 v80, v32, v1
	v_mul_f32_e32 v81, v33, v1
	v_cvt_pk_bf16_f32 v84, v80, v81
	v_mul_f32_e32 v82, v34, v1
	v_mul_f32_e32 v83, v35, v1
	v_cvt_pk_bf16_f32 v85, v82, v83
	v_mul_f32_e32 v80, v36, v1
	v_mul_f32_e32 v81, v37, v1
	v_cvt_pk_bf16_f32 v86, v80, v81
	v_mul_f32_e32 v82, v38, v1
	v_mul_f32_e32 v83, v39, v1
	v_cvt_pk_bf16_f32 v87, v82, v83
	s_nop 1
	v_permlane32_swap_b32_e32 v84, v86
	v_permlane32_swap_b32_e32 v85, v87
	global_store_dwordx4 v[2:3], v[84:87], off offset:128
	v_mul_f32_e32 v80, v40, v1
	v_mul_f32_e32 v81, v41, v1
	v_cvt_pk_bf16_f32 v84, v80, v81
	v_mul_f32_e32 v82, v42, v1
	v_mul_f32_e32 v83, v43, v1
	v_cvt_pk_bf16_f32 v85, v82, v83
	v_mul_f32_e32 v80, v44, v1
	v_mul_f32_e32 v81, v45, v1
	v_cvt_pk_bf16_f32 v86, v80, v81
	v_mul_f32_e32 v82, v46, v1
	v_mul_f32_e32 v83, v47, v1
	v_cvt_pk_bf16_f32 v87, v82, v83
	s_nop 1
	v_permlane32_swap_b32_e32 v84, v86
	v_permlane32_swap_b32_e32 v85, v87
	global_store_dwordx4 v[2:3], v[84:87], off offset:160
	v_mul_f32_e32 v80, v16, v1
	v_mul_f32_e32 v81, v17, v1
	v_cvt_pk_bf16_f32 v84, v80, v81
	v_mul_f32_e32 v82, v18, v1
	v_mul_f32_e32 v83, v19, v1
	v_cvt_pk_bf16_f32 v85, v82, v83
	v_mul_f32_e32 v80, v20, v1
	v_mul_f32_e32 v81, v21, v1
	v_cvt_pk_bf16_f32 v86, v80, v81
	v_mul_f32_e32 v82, v22, v1
	v_mul_f32_e32 v83, v23, v1
	v_cvt_pk_bf16_f32 v87, v82, v83
	s_nop 1
	v_permlane32_swap_b32_e32 v84, v86
	v_permlane32_swap_b32_e32 v85, v87
	global_store_dwordx4 v[2:3], v[84:87], off offset:192
	v_mul_f32_e32 v80, v24, v1
	v_mul_f32_e32 v81, v25, v1
	v_cvt_pk_bf16_f32 v84, v80, v81
	v_mul_f32_e32 v82, v26, v1
	v_mul_f32_e32 v83, v27, v1
	v_cvt_pk_bf16_f32 v85, v82, v83
	v_mul_f32_e32 v80, v28, v1
	v_mul_f32_e32 v81, v29, v1
	v_cvt_pk_bf16_f32 v86, v80, v81
	v_mul_f32_e32 v82, v30, v1
	v_mul_f32_e32 v83, v31, v1
	v_cvt_pk_bf16_f32 v87, v82, v83
	s_nop 1
	v_permlane32_swap_b32_e32 v84, v86
	v_permlane32_swap_b32_e32 v85, v87
	global_store_dwordx4 v[2:3], v[84:87], off offset:224
	s_cbranch_scc0 .LBB0_1561

; __device__ __forceinline__ unsigned cvt_pk_bf16(float lo, float hi) { unsigned r; asm volatile("v_cvt_pk_bf16_f32 %0, %1, %2" : "=v"(r) : "v"(lo), "v"(hi)); return r; }
; __device__ __forceinline__ void attn_unit(LAS unsigned char* lds, const bf16_t* QK, const bf16_t* VTt, const float* KM, bf16_t* OA, int b, int h, int qb, int tid, int lane, int wave) {
;     ...
;     const float inv = 1.f / (lrun + __shfl_xor(lrun, 32));
;     bf16_t* op = OA + (size_t)(row0 + r32) * D + h * HD + hf * 4;
; #pragma unroll
;     for (int db = 0; db < 4; ++db)
; #pragma unroll
;         for (int rg = 0; rg < 4; ++rg) { u32x2 w; w.x = cvt_pk_bf16(o[db][4 * rg] * inv, o[db][4 * rg + 1] * inv); w.y = cvt_pk_bf16(o[db][4 * rg + 2] * inv, o[db][4 * rg + 3] * inv);
;             *(u32x2*)(op + db * 32 + rg * 8) = w; }
.LBB0_1540:
	ds_bpermute_b32 v1, v219, v226
	s_and_b32 s0, s65, 3
	s_lshl_b32 s20, s0, 8
	s_lshl_b32 s44, s44, 1
	v_mov_b32_e32 v211, v0
	s_waitcnt lgkmcnt(0)
	v_add_f32_e32 v1, v226, v1
	v_div_scale_f32 v2, s[0:1], v1, v1, 1.0
	v_rcp_f32_e32 v3, v2
	v_div_scale_f32 v4, vcc, 1.0, v1, 1.0
	s_addk_i32 s20, 0x100
	v_fma_f32 v5, -v2, v3, 1.0
	v_fmac_f32_e32 v3, v5, v3
	v_mul_f32_e32 v5, v4, v3
	v_fma_f32 v6, -v2, v5, v4
	v_fmac_f32_e32 v5, v6, v3
	v_fma_f32 v2, -v2, v5, v4
	v_div_fmas_f32 v2, v2, v3, v5
	v_div_fixup_f32 v1, v2, v1, 1.0
	v_lshlrev_b64 v[2:3], 11, v[216:217]
	v_lshl_add_u64 v[2:3], s[18:19], 0, v[2:3]
	v_lshl_add_u64 v[2:3], v[2:3], 0, s[44:45]
	v_lshl_add_u64 v[2:3], v[2:3], 0, v[210:211]
	v_and_b32_e32 v88, 32, v196
	v_lshrrev_b32_e32 v88, 2, v88
	v_mov_b32_e32 v89, 0
	v_lshl_add_u64 v[2:3], v[2:3], 0, v[88:89]
	v_mul_f32_e32 v80, v64, v1
	v_mul_f32_e32 v81, v65, v1
	v_cvt_pk_bf16_f32 v84, v80, v81
	v_mul_f32_e32 v82, v66, v1
	v_mul_f32_e32 v83, v67, v1
	v_cvt_pk_bf16_f32 v85, v82, v83
	v_mul_f32_e32 v80, v68, v1
	v_mul_f32_e32 v81, v69, v1
	v_cvt_pk_bf16_f32 v86, v80, v81
	v_mul_f32_e32 v82, v70, v1
	v_mul_f32_e32 v83, v71, v1
	v_cvt_pk_bf16_f32 v87, v82, v83
	s_nop 1
	v_permlane32_swap_b32_e32 v84, v86
	v_permlane32_swap_b32_e32 v85, v87
	global_store_dwordx4 v[2:3], v[84:87], off
	s_lshl_b32 s12, s66, 8
	s_lshl_b32 s34, s66, 2
	s_lshl_b32 s0, s66, 20
	s_add_u32 s0, s67, s0
	s_addc_u32 s1, s68, 0
	s_add_u32 s13, s0, 0x800
	s_addc_u32 s14, s1, 0
	s_lshl_b32 s0, s66, 16
	s_add_u32 s0, s69, s0
	s_addc_u32 s1, s70, 0
	s_and_b64 s[10:11], s[4:5], exec
	s_cselect_b32 s11, s14, s1
	s_cselect_b32 s10, s13, s0
	v_mul_f32_e32 v80, v72, v1
	v_mul_f32_e32 v81, v73, v1
	v_cvt_pk_bf16_f32 v84, v80, v81
	v_mul_f32_e32 v82, v74, v1
	v_mul_f32_e32 v83, v75, v1
	v_cvt_pk_bf16_f32 v85, v82, v83
	v_mul_f32_e32 v80, v76, v1
	v_mul_f32_e32 v81, v77, v1
	v_cvt_pk_bf16_f32 v86, v80, v81
	v_mul_f32_e32 v82, v78, v1
	v_mul_f32_e32 v83, v79, v1
	v_cvt_pk_bf16_f32 v87, v82, v83
	s_nop 1
	v_permlane32_swap_b32_e32 v84, v86
	v_permlane32_swap_b32_e32 v85, v87
	global_store_dwordx4 v[2:3], v[84:87], off offset:32
	v_mul_f32_e32 v80, v48, v1
	v_mul_f32_e32 v81, v49, v1
	v_cvt_pk_bf16_f32 v84, v80, v81
	v_mul_f32_e32 v82, v50, v1
	v_mul_f32_e32 v83, v51, v1
	v_cvt_pk_bf16_f32 v85, v82, v83
	v_mul_f32_e32 v80, v52, v1
	v_mul_f32_e32 v81, v53, v1
	v_cvt_pk_bf16_f32 v86, v80, v81
	v_mul_f32_e32 v82, v54, v1
	v_mul_f32_e32 v83, v55, v1
	v_cvt_pk_bf16_f32 v87, v82, v83
	s_nop 1
	v_permlane32_swap_b32_e32 v84, v86
	v_permlane32_swap_b32_e32 v85, v87
	global_store_dwordx4 v[2:3], v[84:87], off offset:64
	v_mul_f32_e32 v80, v56, v1
	v_mul_f32_e32 v81, v57, v1
	v_cvt_pk_bf16_f32 v84, v80, v81
	v_mul_f32_e32 v82, v58, v1
	v_mul_f32_e32 v83, v59, v1
	v_cvt_pk_bf16_f32 v85, v82, v83
	v_mul_f32_e32 v80, v60, v1
	v_mul_f32_e32 v81, v61, v1
	v_cvt_pk_bf16_f32 v86, v80, v81
	v_mul_f32_e32 v82, v62, v1
	v_mul_f32_e32 v83, v63, v1
	v_cvt_pk_bf16_f32 v87, v82, v83
	s_nop 1
	v_permlane32_swap_b32_e32 v84, v86
	v_permlane32_swap_b32_e32 v85, v87
	global_store_dwordx4 v[2:3], v[84:87], off offset:96
	v_mul_f32_e32 v80, v32, v1
	v_mul_f32_e32 v81, v33, v1
	v_cvt_pk_bf16_f32 v84, v80, v81
	v_mul_f32_e32 v82, v34, v1
	v_mul_f32_e32 v83, v35, v1
	v_cvt_pk_bf16_f32 v85, v82, v83
	v_mul_f32_e32 v80, v36, v1
	v_mul_f32_e32 v81, v37, v1
	v_cvt_pk_bf16_f32 v86, v80, v81
	v_mul_f32_e32 v82, v38, v1
	v_mul_f32_e32 v83, v39, v1
	v_cvt_pk_bf16_f32 v87, v82, v83
	s_nop 1
	v_permlane32_swap_b32_e32 v84, v86
	v_permlane32_swap_b32_e32 v85, v87
	global_store_dwordx4 v[2:3], v[84:87], off offset:128
	v_mul_f32_e32 v80, v40, v1
	v_mul_f32_e32 v81, v41, v1
	v_cvt_pk_bf16_f32 v84, v80, v81
	v_mul_f32_e32 v82, v42, v1
	v_mul_f32_e32 v83, v43, v1
	v_cvt_pk_bf16_f32 v85, v82, v83
	v_mul_f32_e32 v80, v44, v1
	v_mul_f32_e32 v81, v45, v1
	v_cvt_pk_bf16_f32 v86, v80, v81
	v_mul_f32_e32 v82, v46, v1
	v_mul_f32_e32 v83, v47, v1
	v_cvt_pk_bf16_f32 v87, v82, v83
	s_nop 1
	v_permlane32_swap_b32_e32 v84, v86
	v_permlane32_swap_b32_e32 v85, v87
	global_store_dwordx4 v[2:3], v[84:87], off offset:160
	v_mul_f32_e32 v80, v16, v1
	v_mul_f32_e32 v81, v17, v1
	v_cvt_pk_bf16_f32 v84, v80, v81
	v_mul_f32_e32 v82, v18, v1
	v_mul_f32_e32 v83, v19, v1
	v_cvt_pk_bf16_f32 v85, v82, v83
	v_mul_f32_e32 v80, v20, v1
	v_mul_f32_e32 v81, v21, v1
	v_cvt_pk_bf16_f32 v86, v80, v81
	v_mul_f32_e32 v82, v22, v1
	v_mul_f32_e32 v83, v23, v1
	v_cvt_pk_bf16_f32 v87, v82, v83
	s_nop 1
	v_permlane32_swap_b32_e32 v84, v86
	v_permlane32_swap_b32_e32 v85, v87
; __device__ __forceinline__ void attn_unit(LAS unsigned char* lds, const bf16_t* QK, const bf16_t* VTt, const float* KM, bf16_t* OA, int b, int h, int qb, int tid, int lane, int wave) {
;     ...
;     ATT_DMA(0, 0); ATT_DMA(1, 1);
;     bf16x8 qf[8];
;     { const bf16_t* qp = QK + (size_t)(row0 + r32) * 2048 + h * HD + hf * 8;
; #pragma unroll
;       for (int ks = 0; ks < 8; ++ks) qf[ks] = *(const bf16x8*)(qp + ks * 16); }
;     unsigned sel = (1u << qb) - 1u;
;     if (qb > 3) {
;         float gate[7];
; #pragma unroll
;         for (int n = 0; n < 7; ++n) { gate[n] = -INFINITY;
;             if (n < qb) { const float* kp = KM + ((size_t)(b * NH + h) * 8 + n) * HD + hf * 8; float s = 0.f;
; #pragma unroll
;                 for (int ks = 0; ks < 8; ++ks) { const f32x4 k0 = *(const f32x4*)(kp + ks * 16), k1 = *(const f32x4*)(kp + ks * 16 + 4); const u32x4 q = __builtin_bit_cast(u32x4, qf[ks]);
;                     s += bf_lo(q.x) * k0.x + bf_hi(q.x) * k0.y + bf_lo(q.y) * k0.z + bf_hi(q.y) * k0.w + bf_lo(q.z) * k1.x + bf_hi(q.z) * k1.y + bf_lo(q.w) * k1.z + bf_hi(q.w) * k1.w; }
;                 gate[n] = s + __shfl_xor(s, 32); } }
;         sel = 0u;
; #pragma unroll
;         for (int rnd = 0; rnd < 3; ++rnd) { float best = -INFINITY; int bi = 0;
; #pragma unroll
;             for (int n = 0; n < 7; ++n) { const bool ok = (n < qb) && !((sel >> n) & 1u) && (gate[n] > best); best = ok ? gate[n] : best; bi = ok ? n : bi; }
;             sel |= 1u << bi; }
;     }
;     f32x16 o[4];
; #pragma unroll
;     for (int db = 0; db < 4; ++db)
; #pragma unroll
;         for (int i = 0; i < 16; ++i) o[db][i] = 0.f;
;     float mrun = -1e30f, lrun = 0.f;
;     const int pi_r = ((r32 >> 2) & 1) * 16 + (r32 >> 3) * 4 + (r32 & 3);
;     const int qq = wave * 32 + r32;
;     const unsigned kread = pi_r * ATT_KROW + hf * 16, vread = ATT_KB + r32 * ATT_VROW + hf * 32;
;     asm volatile("s_waitcnt vmcnt(0)" ::: "memory"); __builtin_amdgcn_s_barrier(); asm volatile("" ::: "memory");
;     int st = 0;
;     ...
; #pragma unroll
;         for (int rg = 0; rg < 4; ++rg) { u32x2 w; w.x = cvt_pk_bf16(o[db][4 * rg] * inv, o[db][4 * rg + 1] * inv); w.y = cvt_pk_bf16(o[db][4 * rg + 2] * inv, o[db][4 * rg + 3] * inv);
;             *(u32x2*)(op + db * 32 + rg * 8) = w; }
	global_store_dwordx4 v[2:3], v[84:87], off offset:192
	v_mul_f32_e32 v80, v24, v1
	v_mul_f32_e32 v81, v25, v1
	v_cvt_pk_bf16_f32 v84, v80, v81
	v_mul_f32_e32 v82, v26, v1
	v_mul_f32_e32 v83, v27, v1
	v_cvt_pk_bf16_f32 v85, v82, v83
	v_mul_f32_e32 v80, v28, v1
	v_mul_f32_e32 v81, v29, v1
	v_cvt_pk_bf16_f32 v86, v80, v81
	v_mul_f32_e32 v82, v30, v1
	v_mul_f32_e32 v83, v31, v1
	v_cvt_pk_bf16_f32 v87, v82, v83
	s_nop 1
	v_permlane32_swap_b32_e32 v84, v86
	v_permlane32_swap_b32_e32 v85, v87
	global_store_dwordx4 v[2:3], v[84:87], off offset:224
	v_lshl_add_u64 v[2:3], s[10:11], 0, v[204:205]
	s_and_b64 s[10:11], s[6:7], exec
	s_mov_b32 m0, s54
	s_cselect_b32 s11, s14, s1
	s_cselect_b32 s10, s13, s0
	global_load_lds_dwordx4 v[2:3], off
	v_lshl_add_u64 v[2:3], s[10:11], 0, v[206:207]
	s_and_b64 s[10:11], s[8:9], exec
	s_mov_b32 m0, s55
	s_cselect_b32 s11, s14, s1
	s_cselect_b32 s10, s13, s0
	global_load_lds_dwordx4 v[2:3], off
	v_lshl_add_u64 v[2:3], s[10:11], 0, v[208:209]
	s_mov_b32 m0, s56
	v_add_u32_e32 v216, s12, v213
	global_load_lds_dwordx4 v[2:3], off
	v_lshl_add_u64 v[2:3], s[0:1], 0, v[198:199]
	s_mov_b32 m0, s57
	v_ashrrev_i32_e32 v217, 31, v216
	global_load_lds_dwordx4 v[2:3], off
	v_lshl_add_u64 v[2:3], s[0:1], 0, v[200:201]
	s_or_b32 s0, s12, 64
	s_lshl_b32 s1, s0, 12
	s_add_u32 s1, s67, s1
	s_addc_u32 s10, s68, 0
	s_add_u32 s13, s1, 0x800
	s_addc_u32 s14, s10, 0
	s_lshl_b32 s0, s0, 8
	s_add_u32 s0, s69, s0
	s_addc_u32 s1, s70, 0
	s_and_b64 s[10:11], s[4:5], exec
	s_mov_b32 m0, s58
	s_cselect_b32 s11, s14, s1
	s_cselect_b32 s10, s13, s0
	global_load_lds_dwordx4 v[2:3], off
	v_lshl_add_u64 v[2:3], s[10:11], 0, v[204:205]
	s_and_b64 s[10:11], s[6:7], exec
	s_mov_b32 m0, s59
	s_cselect_b32 s11, s14, s1
	s_cselect_b32 s10, s13, s0
	global_load_lds_dwordx4 v[2:3], off
	v_lshl_add_u64 v[2:3], s[10:11], 0, v[206:207]
	s_and_b64 s[10:11], s[8:9], exec
	s_mov_b32 m0, s60
	s_cselect_b32 s11, s14, s1
	s_cselect_b32 s10, s13, s0
	global_load_lds_dwordx4 v[2:3], off
	v_lshl_add_u64 v[2:3], s[10:11], 0, v[208:209]
	s_mov_b32 m0, s61
	v_mov_b32_e32 v213, v0
	global_load_lds_dwordx4 v[2:3], off
	v_lshl_add_u64 v[2:3], s[0:1], 0, v[198:199]
	s_mov_b32 m0, s62
	v_mov_b32_e32 v14, v0
	global_load_lds_dwordx4 v[2:3], off
	v_lshl_add_u64 v[2:3], s[0:1], 0, v[200:201]
	s_mov_b32 m0, s63
	v_mov_b32_e32 v15, v0
	global_load_lds_dwordx4 v[2:3], off
	v_lshlrev_b64 v[2:3], 12, v[216:217]
	v_lshl_add_u64 v[2:3], s[40:41], 0, v[2:3]
	v_lshl_add_u64 v[2:3], v[2:3], 0, s[44:45]
	v_lshl_add_u64 v[2:3], v[2:3], 0, v[212:213]
	global_load_dwordx4 v[112:115], v[2:3], off
	global_load_dwordx4 v[116:119], v[2:3], off offset:32
	global_load_dwordx4 v[120:123], v[2:3], off offset:64
	global_load_dwordx4 v[124:127], v[2:3], off offset:96
	global_load_dwordx4 v[128:131], v[2:3], off offset:128
	global_load_dwordx4 v[132:135], v[2:3], off offset:160
	global_load_dwordx4 v[136:139], v[2:3], off offset:192
	global_load_dwordx4 v[140:143], v[2:3], off offset:224
	s_waitcnt vmcnt(0)
	s_barrier
	v_mov_b32_e32 v1, v0
	v_mov_b32_e32 v2, v0
	v_mov_b32_e32 v3, v0
	v_mov_b32_e32 v4, v0
	v_mov_b32_e32 v5, v0
	v_mov_b32_e32 v6, v0
	v_mov_b32_e32 v7, v0
	v_mov_b32_e32 v8, v0
	v_mov_b32_e32 v9, v0
	v_mov_b32_e32 v10, v0
	v_mov_b32_e32 v11, v0
	v_mov_b32_e32 v12, v0
	v_mov_b32_e32 v13, v0
	v_mov_b64_e32 v[30:31], v[14:15]
	v_mov_b64_e32 v[46:47], v[14:15]
	v_mov_b64_e32 v[62:63], v[14:15]
	v_mov_b64_e32 v[78:79], v[14:15]
	s_mov_b32 s21, 3
	s_add_i32 s34, s34, 4
	s_mov_b32 s35, 0
	v_mov_b32_e32 v213, 0xf149f2ca
	v_mov_b32_e32 v211, 0
	v_mov_b64_e32 v[28:29], v[12:13]
	v_mov_b64_e32 v[26:27], v[10:11]
	v_mov_b64_e32 v[24:25], v[8:9]
	v_mov_b64_e32 v[22:23], v[6:7]
	v_mov_b64_e32 v[20:21], v[4:5]
	v_mov_b64_e32 v[18:19], v[2:3]
	v_mov_b64_e32 v[16:17], v[0:1]
	v_mov_b64_e32 v[44:45], v[12:13]
	v_mov_b64_e32 v[42:43], v[10:11]
	v_mov_b64_e32 v[40:41], v[8:9]
	v_mov_b64_e32 v[38:39], v[6:7]
	v_mov_b64_e32 v[36:37], v[4:5]
	v_mov_b64_e32 v[34:35], v[2:3]
	v_mov_b64_e32 v[32:33], v[0:1]
	v_mov_b64_e32 v[60:61], v[12:13]
	v_mov_b64_e32 v[58:59], v[10:11]
	v_mov_b64_e32 v[56:57], v[8:9]
	v_mov_b64_e32 v[54:55], v[6:7]
	v_mov_b64_e32 v[52:53], v[4:5]
	v_mov_b64_e32 v[50:51], v[2:3]
	v_mov_b64_e32 v[48:49], v[0:1]
	v_mov_b64_e32 v[76:77], v[12:13]
	v_mov_b64_e32 v[74:75], v[10:11]
	v_mov_b64_e32 v[72:73], v[8:9]
	v_mov_b64_e32 v[70:71], v[6:7]
	v_mov_b64_e32 v[68:69], v[4:5]
	v_mov_b64_e32 v[66:67], v[2:3]
	v_mov_b64_e32 v[64:65], v[0:1]
	s_mov_b32 s46, 0
	s_waitcnt vmcnt(0)
	s_branch .LBB0_1542
